# P1 epilogue: LDS-staged whole-row stores in two halves (second half's conversion overlaps the first half's store drain)
# baseline (speedup 1.0000x reference)
; DEVINL float sigm(float x) { return 1.f / (1.f + __expf(-x)); }
; template <int EPI, bool GATHER>
; DEVINL void gemm_tile(const Params& p, const u16* __restrict__ A, int lda, const int* __restrict__ rowidx,
;                       const u16* __restrict__ Bt, int ldb, int K, int brow, int bcol, int orow, int ocol) {
;     ...
;   const int row0 = orow + wr * 64 + fq * 4;
;   const int col0 = ocol + wc * 32 + fr;
;   const bool odd = (fr & 1) != 0;
;   const int colp = col0 - (odd ? 1 : 0);
; #pragma unroll
;   for (int ai = 0; ai < 2; ++ai)
; #pragma unroll
;     for (int m = 0; m < 4; ++m) {
;       const int rA = row0 + ai * HALF + m * 16 + (odd ? 2 : 0);
;       float gate[2] = {0.f, 0.f};
;       if (EPI == EPI_MOE2) { gate[0] = ((const float*)(ws + O_SELG))[rA]; gate[1] = ((const float*)(ws + O_SELG))[rA + 1]; }
; #pragma unroll
;       for (int bj = 0; bj < (EPI == EPI_HID ? 1 : 2); ++bj)
; #pragma unroll
;         for (int n = 0; n < 2; ++n) {
;           const int cc = bj * HALF + n * 16;
;           f32x4 v = acc[ai][bj][m][n];
;           if (EPI == EPI_HID) {
; #pragma unroll
;             for (int j = 0; j < 4; ++j) { const float a1 = acc[ai][0][m][n][j], a3 = acc[ai][1][m][n][j]; v[j] = a1 * sigm(a1) * a3; }
;           }
;           float lo[2], hi[2];
;           xchg_pairs(v, odd, lo, hi);
; #pragma unroll
;           for (int k = 0; k < 2; ++k) {
;             const unsigned row = (unsigned)(rA + k);
;             if (EPI == EPI_HID) {
;               *(unsigned*)(ws + O_HID + (row * 1024u + (unsigned)(colp + cc)) * 2u) = pk2(lo[k], hi[k]);
;             } else if (EPI == EPI_COLS) {
;               *(unsigned*)(ws + O_COLS + (row * (unsigned)NCP + (unsigned)(colp + cc)) * 2u) = pk2(lo[k], hi[k]);
.LBB0_223:
	s_or_b64 exec, exec, s[6:7]
	v_and_b32_e32 v128, 63, v189
	v_lshrrev_b32_e32 v129, 6, v189
	v_and_b32_e32 v135, 15, v128
	v_lshrrev_b32_e32 v136, 4, v128
	v_and_b32_e32 v137, 1, v135
	v_lshrrev_b32_e32 v138, 2, v129
	v_and_b32_e32 v139, 3, v129
	v_lshlrev_b32_e32 v138, 6, v138
	v_lshl_add_u32 v138, v136, 2, v138
	v_lshl_add_u32 v138, v137, 1, v138
	v_mul_u32_u24_e32 v130, 528, v138
	v_lshl_add_u32 v139, v139, 5, v135
	v_sub_u32_e32 v139, v139, v137
	v_lshl_add_u32 v130, v139, 1, v130
	v_add_u32_e32 v130, 16, v130
	v_add_u32_e32 v131, 67584, v130
	v_cmp_eq_u32_e32 vcc, 0, v137
	v_lshrrev_b32_e32 v141, 5, v189
	v_and_b32_e32 v142, 31, v189
	v_mul_u32_u24_e32 v132, 528, v141
	v_lshl_add_u32 v132, v142, 4, v132
	v_add_u32_e32 v132, 16, v132
	v_add_u32_e32 v133, 67584, v132
	v_add_u32_e32 v141, s48, v141
	s_movk_i32 s4, 0x5400
	v_mul_lo_u32 v134, v141, s4
	v_lshl_add_u32 v142, v142, 3, s78
	v_lshl_add_u32 v134, v142, 1, v134
	s_barrier
	v_add_u32_e32 v148, 0x54000, v134
	v_add_u32_e32 v149, 0xa8000, v134
	v_add_u32_e32 v150, 0xfc000, v134
	v_add_u32_e32 v151, 0x150000, v134
	v_add_u32_e32 v152, 0x1a4000, v134
	v_add_u32_e32 v153, 0x1f8000, v134
	v_add_u32_e32 v154, 0x24c000, v134
	v_add_u32_e32 v155, 0x2a0000, v134
	v_add_u32_e32 v156, 0x2f4000, v134
	v_add_u32_e32 v157, 0x348000, v134
	v_add_u32_e32 v158, 0x39c000, v134
	v_add_u32_e32 v159, 0x3f0000, v134
	v_add_u32_e32 v160, 0x444000, v134
	v_add_u32_e32 v161, 0x498000, v134
	v_add_u32_e32 v162, 0x4ec000, v134
	v_cndmask_b32_e32 v143, v124, v126, vcc
	v_cndmask_b32_e32 v144, v125, v127, vcc
	v_cndmask_b32_e32 v145, v116, v118, vcc
	v_cndmask_b32_e32 v146, v117, v119, vcc
	v_mov_b32_dpp v143, v143 quad_perm:[1,0,3,2] row_mask:0xf bank_mask:0xf bound_ctrl:1
	v_mov_b32_dpp v144, v144 quad_perm:[1,0,3,2] row_mask:0xf bank_mask:0xf bound_ctrl:1
	v_mov_b32_dpp v145, v145 quad_perm:[1,0,3,2] row_mask:0xf bank_mask:0xf bound_ctrl:1
	v_mov_b32_dpp v146, v146 quad_perm:[1,0,3,2] row_mask:0xf bank_mask:0xf bound_ctrl:1
	v_cndmask_b32_e32 v124, v143, v124, vcc
	v_cndmask_b32_e32 v126, v126, v143, vcc
	v_cndmask_b32_e32 v125, v144, v125, vcc
	v_cndmask_b32_e32 v127, v127, v144, vcc
	v_cvt_pk_bf16_f32 v124, v124, v126
	v_cvt_pk_bf16_f32 v125, v125, v127
	ds_write_b32 v130, v124
	ds_write_b32 v130, v125 offset:528
	v_cndmask_b32_e32 v116, v145, v116, vcc
	v_cndmask_b32_e32 v118, v118, v145, vcc
	v_cndmask_b32_e32 v117, v146, v117, vcc
	v_cndmask_b32_e32 v119, v119, v146, vcc
	v_cvt_pk_bf16_f32 v116, v116, v118
	v_cvt_pk_bf16_f32 v117, v117, v119
	ds_write_b32 v130, v116 offset:32
	ds_write_b32 v130, v117 offset:560
	v_cndmask_b32_e32 v143, v120, v122, vcc
	v_cndmask_b32_e32 v144, v121, v123, vcc
	v_cndmask_b32_e32 v145, v112, v114, vcc
	v_cndmask_b32_e32 v146, v113, v115, vcc
	v_mov_b32_dpp v143, v143 quad_perm:[1,0,3,2] row_mask:0xf bank_mask:0xf bound_ctrl:1
	v_mov_b32_dpp v144, v144 quad_perm:[1,0,3,2] row_mask:0xf bank_mask:0xf bound_ctrl:1
	v_mov_b32_dpp v145, v145 quad_perm:[1,0,3,2] row_mask:0xf bank_mask:0xf bound_ctrl:1
	v_mov_b32_dpp v146, v146 quad_perm:[1,0,3,2] row_mask:0xf bank_mask:0xf bound_ctrl:1
	v_cndmask_b32_e32 v120, v143, v120, vcc
	v_cndmask_b32_e32 v122, v122, v143, vcc
	v_cndmask_b32_e32 v121, v144, v121, vcc
	v_cndmask_b32_e32 v123, v123, v144, vcc
	v_cvt_pk_bf16_f32 v120, v120, v122
	v_cvt_pk_bf16_f32 v121, v121, v123
	ds_write_b32 v130, v120 offset:256
	ds_write_b32 v130, v121 offset:784
	v_cndmask_b32_e32 v112, v145, v112, vcc
	v_cndmask_b32_e32 v114, v114, v145, vcc
	v_cndmask_b32_e32 v113, v146, v113, vcc
	v_cndmask_b32_e32 v115, v115, v146, vcc
	v_cvt_pk_bf16_f32 v112, v112, v114
	v_cvt_pk_bf16_f32 v113, v113, v115
	ds_write_b32 v130, v112 offset:288
	ds_write_b32 v130, v113 offset:816
	v_cndmask_b32_e32 v143, v108, v110, vcc
	v_cndmask_b32_e32 v144, v109, v111, vcc
	v_cndmask_b32_e32 v145, v100, v102, vcc
	v_cndmask_b32_e32 v146, v101, v103, vcc
	v_mov_b32_dpp v143, v143 quad_perm:[1,0,3,2] row_mask:0xf bank_mask:0xf bound_ctrl:1
	v_mov_b32_dpp v144, v144 quad_perm:[1,0,3,2] row_mask:0xf bank_mask:0xf bound_ctrl:1
	v_mov_b32_dpp v145, v145 quad_perm:[1,0,3,2] row_mask:0xf bank_mask:0xf bound_ctrl:1
	v_mov_b32_dpp v146, v146 quad_perm:[1,0,3,2] row_mask:0xf bank_mask:0xf bound_ctrl:1
	v_cndmask_b32_e32 v108, v143, v108, vcc
	v_cndmask_b32_e32 v110, v110, v143, vcc
	v_cndmask_b32_e32 v109, v144, v109, vcc
	v_cndmask_b32_e32 v111, v111, v144, vcc
	v_cvt_pk_bf16_f32 v108, v108, v110
	v_cvt_pk_bf16_f32 v109, v109, v111
	ds_write_b32 v130, v108 offset:8448
	ds_write_b32 v130, v109 offset:8976
	v_cndmask_b32_e32 v100, v145, v100, vcc
	v_cndmask_b32_e32 v102, v102, v145, vcc
	v_cndmask_b32_e32 v101, v146, v101, vcc
	v_cndmask_b32_e32 v103, v103, v146, vcc
	v_cvt_pk_bf16_f32 v100, v100, v102
	v_cvt_pk_bf16_f32 v101, v101, v103
	ds_write_b32 v130, v100 offset:8480
	ds_write_b32 v130, v101 offset:9008
	v_cndmask_b32_e32 v143, v104, v106, vcc
	v_cndmask_b32_e32 v144, v105, v107, vcc
	v_cndmask_b32_e32 v145, v96, v98, vcc
	v_cndmask_b32_e32 v146, v97, v99, vcc
	v_mov_b32_dpp v143, v143 quad_perm:[1,0,3,2] row_mask:0xf bank_mask:0xf bound_ctrl:1
	v_mov_b32_dpp v144, v144 quad_perm:[1,0,3,2] row_mask:0xf bank_mask:0xf bound_ctrl:1
	v_mov_b32_dpp v145, v145 quad_perm:[1,0,3,2] row_mask:0xf bank_mask:0xf bound_ctrl:1
	v_mov_b32_dpp v146, v146 quad_perm:[1,0,3,2] row_mask:0xf bank_mask:0xf bound_ctrl:1
	v_cndmask_b32_e32 v104, v143, v104, vcc
	v_cndmask_b32_e32 v106, v106, v143, vcc
	v_cndmask_b32_e32 v105, v144, v105, vcc
	v_cndmask_b32_e32 v107, v107, v144, vcc
	v_cvt_pk_bf16_f32 v104, v104, v106
	v_cvt_pk_bf16_f32 v105, v105, v107
	ds_write_b32 v130, v104 offset:8704
; DEVINL float sigm(float x) { return 1.f / (1.f + __expf(-x)); }
; template <int EPI, bool GATHER>
; DEVINL void gemm_tile(const Params& p, const u16* __restrict__ A, int lda, const int* __restrict__ rowidx,
;                       const u16* __restrict__ Bt, int ldb, int K, int brow, int bcol, int orow, int ocol) {
;     ...
;         for (int n = 0; n < 2; ++n) {
;           const int cc = bj * HALF + n * 16;
;           f32x4 v = acc[ai][bj][m][n];
;           if (EPI == EPI_HID) {
; #pragma unroll
;             for (int j = 0; j < 4; ++j) { const float a1 = acc[ai][0][m][n][j], a3 = acc[ai][1][m][n][j]; v[j] = a1 * sigm(a1) * a3; }
;           }
;           float lo[2], hi[2];
;           xchg_pairs(v, odd, lo, hi);
; #pragma unroll
;           for (int k = 0; k < 2; ++k) {
;             const unsigned row = (unsigned)(rA + k);
;             if (EPI == EPI_HID) {
;               *(unsigned*)(ws + O_HID + (row * 1024u + (unsigned)(colp + cc)) * 2u) = pk2(lo[k], hi[k]);
;             } else if (EPI == EPI_COLS) {
;               *(unsigned*)(ws + O_COLS + (row * (unsigned)NCP + (unsigned)(colp + cc)) * 2u) = pk2(lo[k], hi[k]);
	ds_write_b32 v130, v105 offset:9232
	v_cndmask_b32_e32 v96, v145, v96, vcc
	v_cndmask_b32_e32 v98, v98, v145, vcc
	v_cndmask_b32_e32 v97, v146, v97, vcc
	v_cndmask_b32_e32 v99, v99, v146, vcc
	v_cvt_pk_bf16_f32 v96, v96, v98
	v_cvt_pk_bf16_f32 v97, v97, v99
	ds_write_b32 v130, v96 offset:8736
	ds_write_b32 v130, v97 offset:9264
	v_cndmask_b32_e32 v143, v92, v94, vcc
	v_cndmask_b32_e32 v144, v93, v95, vcc
	v_cndmask_b32_e32 v145, v84, v86, vcc
	v_cndmask_b32_e32 v146, v85, v87, vcc
	v_mov_b32_dpp v143, v143 quad_perm:[1,0,3,2] row_mask:0xf bank_mask:0xf bound_ctrl:1
	v_mov_b32_dpp v144, v144 quad_perm:[1,0,3,2] row_mask:0xf bank_mask:0xf bound_ctrl:1
	v_mov_b32_dpp v145, v145 quad_perm:[1,0,3,2] row_mask:0xf bank_mask:0xf bound_ctrl:1
	v_mov_b32_dpp v146, v146 quad_perm:[1,0,3,2] row_mask:0xf bank_mask:0xf bound_ctrl:1
	v_cndmask_b32_e32 v92, v143, v92, vcc
	v_cndmask_b32_e32 v94, v94, v143, vcc
	v_cndmask_b32_e32 v93, v144, v93, vcc
	v_cndmask_b32_e32 v95, v95, v144, vcc
	v_cvt_pk_bf16_f32 v92, v92, v94
	v_cvt_pk_bf16_f32 v93, v93, v95
	ds_write_b32 v130, v92 offset:16896
	ds_write_b32 v130, v93 offset:17424
	v_cndmask_b32_e32 v84, v145, v84, vcc
	v_cndmask_b32_e32 v86, v86, v145, vcc
	v_cndmask_b32_e32 v85, v146, v85, vcc
	v_cndmask_b32_e32 v87, v87, v146, vcc
	v_cvt_pk_bf16_f32 v84, v84, v86
	v_cvt_pk_bf16_f32 v85, v85, v87
	ds_write_b32 v130, v84 offset:16928
	ds_write_b32 v130, v85 offset:17456
	v_cndmask_b32_e32 v143, v88, v90, vcc
	v_cndmask_b32_e32 v144, v89, v91, vcc
	v_cndmask_b32_e32 v145, v80, v82, vcc
	v_cndmask_b32_e32 v146, v81, v83, vcc
	v_mov_b32_dpp v143, v143 quad_perm:[1,0,3,2] row_mask:0xf bank_mask:0xf bound_ctrl:1
	v_mov_b32_dpp v144, v144 quad_perm:[1,0,3,2] row_mask:0xf bank_mask:0xf bound_ctrl:1
	v_mov_b32_dpp v145, v145 quad_perm:[1,0,3,2] row_mask:0xf bank_mask:0xf bound_ctrl:1
	v_mov_b32_dpp v146, v146 quad_perm:[1,0,3,2] row_mask:0xf bank_mask:0xf bound_ctrl:1
	v_cndmask_b32_e32 v88, v143, v88, vcc
	v_cndmask_b32_e32 v90, v90, v143, vcc
	v_cndmask_b32_e32 v89, v144, v89, vcc
	v_cndmask_b32_e32 v91, v91, v144, vcc
	v_cvt_pk_bf16_f32 v88, v88, v90
	v_cvt_pk_bf16_f32 v89, v89, v91
	ds_write_b32 v130, v88 offset:17152
	ds_write_b32 v130, v89 offset:17680
	v_cndmask_b32_e32 v80, v145, v80, vcc
	v_cndmask_b32_e32 v82, v82, v145, vcc
	v_cndmask_b32_e32 v81, v146, v81, vcc
	v_cndmask_b32_e32 v83, v83, v146, vcc
	v_cvt_pk_bf16_f32 v80, v80, v82
	v_cvt_pk_bf16_f32 v81, v81, v83
	ds_write_b32 v130, v80 offset:17184
	ds_write_b32 v130, v81 offset:17712
	v_cndmask_b32_e32 v143, v76, v78, vcc
	v_cndmask_b32_e32 v144, v77, v79, vcc
	v_cndmask_b32_e32 v145, v68, v70, vcc
	v_cndmask_b32_e32 v146, v69, v71, vcc
	v_mov_b32_dpp v143, v143 quad_perm:[1,0,3,2] row_mask:0xf bank_mask:0xf bound_ctrl:1
	v_mov_b32_dpp v144, v144 quad_perm:[1,0,3,2] row_mask:0xf bank_mask:0xf bound_ctrl:1
	v_mov_b32_dpp v145, v145 quad_perm:[1,0,3,2] row_mask:0xf bank_mask:0xf bound_ctrl:1
	v_mov_b32_dpp v146, v146 quad_perm:[1,0,3,2] row_mask:0xf bank_mask:0xf bound_ctrl:1
	v_cndmask_b32_e32 v76, v143, v76, vcc
	v_cndmask_b32_e32 v78, v78, v143, vcc
	v_cndmask_b32_e32 v77, v144, v77, vcc
	v_cndmask_b32_e32 v79, v79, v144, vcc
	v_cvt_pk_bf16_f32 v76, v76, v78
	v_cvt_pk_bf16_f32 v77, v77, v79
	ds_write_b32 v130, v76 offset:25344
	ds_write_b32 v130, v77 offset:25872
	v_cndmask_b32_e32 v68, v145, v68, vcc
	v_cndmask_b32_e32 v70, v70, v145, vcc
	v_cndmask_b32_e32 v69, v146, v69, vcc
	v_cndmask_b32_e32 v71, v71, v146, vcc
	v_cvt_pk_bf16_f32 v68, v68, v70
	v_cvt_pk_bf16_f32 v69, v69, v71
	ds_write_b32 v130, v68 offset:25376
	ds_write_b32 v130, v69 offset:25904
	v_cndmask_b32_e32 v143, v72, v74, vcc
	v_cndmask_b32_e32 v144, v73, v75, vcc
	v_cndmask_b32_e32 v145, v60, v62, vcc
	v_cndmask_b32_e32 v146, v61, v63, vcc
	v_mov_b32_dpp v143, v143 quad_perm:[1,0,3,2] row_mask:0xf bank_mask:0xf bound_ctrl:1
	v_mov_b32_dpp v144, v144 quad_perm:[1,0,3,2] row_mask:0xf bank_mask:0xf bound_ctrl:1
	v_mov_b32_dpp v145, v145 quad_perm:[1,0,3,2] row_mask:0xf bank_mask:0xf bound_ctrl:1
	v_mov_b32_dpp v146, v146 quad_perm:[1,0,3,2] row_mask:0xf bank_mask:0xf bound_ctrl:1
	v_cndmask_b32_e32 v72, v143, v72, vcc
	v_cndmask_b32_e32 v74, v74, v143, vcc
	v_cndmask_b32_e32 v73, v144, v73, vcc
	v_cndmask_b32_e32 v75, v75, v144, vcc
	v_cvt_pk_bf16_f32 v72, v72, v74
	v_cvt_pk_bf16_f32 v73, v73, v75
	ds_write_b32 v130, v72 offset:25600
	ds_write_b32 v130, v73 offset:26128
	v_cndmask_b32_e32 v60, v145, v60, vcc
	v_cndmask_b32_e32 v62, v62, v145, vcc
	v_cndmask_b32_e32 v61, v146, v61, vcc
	v_cndmask_b32_e32 v63, v63, v146, vcc
	v_cvt_pk_bf16_f32 v60, v60, v62
	v_cvt_pk_bf16_f32 v61, v61, v63
	ds_write_b32 v130, v60 offset:25632
	ds_write_b32 v130, v61 offset:26160
	s_waitcnt lgkmcnt(0)
	s_barrier
; template <int EPI, bool GATHER>
; DEVINL void gemm_tile(const Params& p, const u16* __restrict__ A, int lda, const int* __restrict__ rowidx,
;                       const u16* __restrict__ Bt, int ldb, int K, int brow, int bcol, int orow, int ocol) {
;     ...
;           xchg_pairs(v, odd, lo, hi);
; #pragma unroll
;           for (int k = 0; k < 2; ++k) {
;             const unsigned row = (unsigned)(rA + k);
;             if (EPI == EPI_HID) {
;               *(unsigned*)(ws + O_HID + (row * 1024u + (unsigned)(colp + cc)) * 2u) = pk2(lo[k], hi[k]);
;             } else if (EPI == EPI_COLS) {
;               *(unsigned*)(ws + O_COLS + (row * (unsigned)NCP + (unsigned)(colp + cc)) * 2u) = pk2(lo[k], hi[k]);
	ds_read_b128 v[60:63], v132
	ds_read_b128 v[68:71], v132 offset:8448
	ds_read_b128 v[72:75], v132 offset:16896
	ds_read_b128 v[76:79], v132 offset:25344
	ds_read_b128 v[80:83], v132 offset:33792
	ds_read_b128 v[84:87], v132 offset:42240
	ds_read_b128 v[88:91], v132 offset:50688
	ds_read_b128 v[92:95], v132 offset:59136
	s_waitcnt lgkmcnt(7)
	global_store_dwordx4 v134, v[60:63], s[0:1]
	s_waitcnt lgkmcnt(6)
	global_store_dwordx4 v148, v[68:71], s[0:1]
	s_waitcnt lgkmcnt(5)
	global_store_dwordx4 v149, v[72:75], s[0:1]
	s_waitcnt lgkmcnt(4)
	global_store_dwordx4 v150, v[76:79], s[0:1]
	s_waitcnt lgkmcnt(3)
	global_store_dwordx4 v151, v[80:83], s[0:1]
	s_waitcnt lgkmcnt(2)
	global_store_dwordx4 v152, v[84:87], s[0:1]
	s_waitcnt lgkmcnt(1)
	global_store_dwordx4 v153, v[88:91], s[0:1]
	s_waitcnt lgkmcnt(0)
	global_store_dwordx4 v154, v[92:95], s[0:1]
	v_cndmask_b32_e32 v143, v64, v66, vcc
	v_cndmask_b32_e32 v144, v65, v67, vcc
	v_cndmask_b32_e32 v145, v52, v54, vcc
	v_cndmask_b32_e32 v146, v53, v55, vcc
	v_mov_b32_dpp v143, v143 quad_perm:[1,0,3,2] row_mask:0xf bank_mask:0xf bound_ctrl:1
	v_mov_b32_dpp v144, v144 quad_perm:[1,0,3,2] row_mask:0xf bank_mask:0xf bound_ctrl:1
	v_mov_b32_dpp v145, v145 quad_perm:[1,0,3,2] row_mask:0xf bank_mask:0xf bound_ctrl:1
	v_mov_b32_dpp v146, v146 quad_perm:[1,0,3,2] row_mask:0xf bank_mask:0xf bound_ctrl:1
	v_cndmask_b32_e32 v64, v143, v64, vcc
	v_cndmask_b32_e32 v66, v66, v143, vcc
	v_cndmask_b32_e32 v65, v144, v65, vcc
	v_cndmask_b32_e32 v67, v67, v144, vcc
	v_cvt_pk_bf16_f32 v64, v64, v66
	v_cvt_pk_bf16_f32 v65, v65, v67
	ds_write_b32 v131, v64
	ds_write_b32 v131, v65 offset:528
	v_cndmask_b32_e32 v52, v145, v52, vcc
	v_cndmask_b32_e32 v54, v54, v145, vcc
	v_cndmask_b32_e32 v53, v146, v53, vcc
	v_cndmask_b32_e32 v55, v55, v146, vcc
	v_cvt_pk_bf16_f32 v52, v52, v54
	v_cvt_pk_bf16_f32 v53, v53, v55
	ds_write_b32 v131, v52 offset:32
	ds_write_b32 v131, v53 offset:560
	v_cndmask_b32_e32 v143, v56, v58, vcc
	v_cndmask_b32_e32 v144, v57, v59, vcc
	v_cndmask_b32_e32 v145, v48, v50, vcc
	v_cndmask_b32_e32 v146, v49, v51, vcc
	v_mov_b32_dpp v143, v143 quad_perm:[1,0,3,2] row_mask:0xf bank_mask:0xf bound_ctrl:1
	v_mov_b32_dpp v144, v144 quad_perm:[1,0,3,2] row_mask:0xf bank_mask:0xf bound_ctrl:1
	v_mov_b32_dpp v145, v145 quad_perm:[1,0,3,2] row_mask:0xf bank_mask:0xf bound_ctrl:1
	v_mov_b32_dpp v146, v146 quad_perm:[1,0,3,2] row_mask:0xf bank_mask:0xf bound_ctrl:1
	v_cndmask_b32_e32 v56, v143, v56, vcc
	v_cndmask_b32_e32 v58, v58, v143, vcc
	v_cndmask_b32_e32 v57, v144, v57, vcc
	v_cndmask_b32_e32 v59, v59, v144, vcc
	v_cvt_pk_bf16_f32 v56, v56, v58
	v_cvt_pk_bf16_f32 v57, v57, v59
	ds_write_b32 v131, v56 offset:256
	ds_write_b32 v131, v57 offset:784
	v_cndmask_b32_e32 v48, v145, v48, vcc
	v_cndmask_b32_e32 v50, v50, v145, vcc
	v_cndmask_b32_e32 v49, v146, v49, vcc
	v_cndmask_b32_e32 v51, v51, v146, vcc
	v_cvt_pk_bf16_f32 v48, v48, v50
	v_cvt_pk_bf16_f32 v49, v49, v51
	ds_write_b32 v131, v48 offset:288
	ds_write_b32 v131, v49 offset:816
	v_cndmask_b32_e32 v143, v44, v46, vcc
	v_cndmask_b32_e32 v144, v45, v47, vcc
	v_cndmask_b32_e32 v145, v36, v38, vcc
	v_cndmask_b32_e32 v146, v37, v39, vcc
	v_mov_b32_dpp v143, v143 quad_perm:[1,0,3,2] row_mask:0xf bank_mask:0xf bound_ctrl:1
	v_mov_b32_dpp v144, v144 quad_perm:[1,0,3,2] row_mask:0xf bank_mask:0xf bound_ctrl:1
	v_mov_b32_dpp v145, v145 quad_perm:[1,0,3,2] row_mask:0xf bank_mask:0xf bound_ctrl:1
	v_mov_b32_dpp v146, v146 quad_perm:[1,0,3,2] row_mask:0xf bank_mask:0xf bound_ctrl:1
	v_cndmask_b32_e32 v44, v143, v44, vcc
	v_cndmask_b32_e32 v46, v46, v143, vcc
	v_cndmask_b32_e32 v45, v144, v45, vcc
	v_cndmask_b32_e32 v47, v47, v144, vcc
	v_cvt_pk_bf16_f32 v44, v44, v46
	v_cvt_pk_bf16_f32 v45, v45, v47
	ds_write_b32 v131, v44 offset:8448
	ds_write_b32 v131, v45 offset:8976
	v_cndmask_b32_e32 v36, v145, v36, vcc
	v_cndmask_b32_e32 v38, v38, v145, vcc
	v_cndmask_b32_e32 v37, v146, v37, vcc
	v_cndmask_b32_e32 v39, v39, v146, vcc
	v_cvt_pk_bf16_f32 v36, v36, v38
	v_cvt_pk_bf16_f32 v37, v37, v39
	ds_write_b32 v131, v36 offset:8480
	ds_write_b32 v131, v37 offset:9008
	v_cndmask_b32_e32 v143, v40, v42, vcc
	v_cndmask_b32_e32 v144, v41, v43, vcc
	v_cndmask_b32_e32 v145, v32, v34, vcc
	v_cndmask_b32_e32 v146, v33, v35, vcc
	v_mov_b32_dpp v143, v143 quad_perm:[1,0,3,2] row_mask:0xf bank_mask:0xf bound_ctrl:1
	v_mov_b32_dpp v144, v144 quad_perm:[1,0,3,2] row_mask:0xf bank_mask:0xf bound_ctrl:1
	v_mov_b32_dpp v145, v145 quad_perm:[1,0,3,2] row_mask:0xf bank_mask:0xf bound_ctrl:1
	v_mov_b32_dpp v146, v146 quad_perm:[1,0,3,2] row_mask:0xf bank_mask:0xf bound_ctrl:1
	v_cndmask_b32_e32 v40, v143, v40, vcc
	v_cndmask_b32_e32 v42, v42, v143, vcc
	v_cndmask_b32_e32 v41, v144, v41, vcc
	v_cndmask_b32_e32 v43, v43, v144, vcc
	v_cvt_pk_bf16_f32 v40, v40, v42
	v_cvt_pk_bf16_f32 v41, v41, v43
	ds_write_b32 v131, v40 offset:8704
	ds_write_b32 v131, v41 offset:9232
	v_cndmask_b32_e32 v32, v145, v32, vcc
	v_cndmask_b32_e32 v34, v34, v145, vcc
	v_cndmask_b32_e32 v33, v146, v33, vcc
	v_cndmask_b32_e32 v35, v35, v146, vcc
	v_cvt_pk_bf16_f32 v32, v32, v34
	v_cvt_pk_bf16_f32 v33, v33, v35
	ds_write_b32 v131, v32 offset:8736
	ds_write_b32 v131, v33 offset:9264
	v_cndmask_b32_e32 v143, v28, v30, vcc
	v_cndmask_b32_e32 v144, v29, v31, vcc
; template <int EPI, bool GATHER>
; DEVINL void gemm_tile(const Params& p, const u16* __restrict__ A, int lda, const int* __restrict__ rowidx,
;                       const u16* __restrict__ Bt, int ldb, int K, int brow, int bcol, int orow, int ocol) {
;     ...
;           xchg_pairs(v, odd, lo, hi);
; #pragma unroll
;           for (int k = 0; k < 2; ++k) {
;             const unsigned row = (unsigned)(rA + k);
;             if (EPI == EPI_HID) {
;               *(unsigned*)(ws + O_HID + (row * 1024u + (unsigned)(colp + cc)) * 2u) = pk2(lo[k], hi[k]);
;             } else if (EPI == EPI_COLS) {
;               *(unsigned*)(ws + O_COLS + (row * (unsigned)NCP + (unsigned)(colp + cc)) * 2u) = pk2(lo[k], hi[k]);
; DEVINL void phase1(const Params& p) {
;     ...
;   for (int t = blockIdx.x; t < ntiles; t += gridDim.x) {
;     int pm = t & 31, pn = t >> 5;
;     gemm_tile<EPI_COLS, false>(p, A, 2048, nullptr, Bt, 2048, 2048, pm * 256, pn * 256, pm * 256, pn * 256);
	v_cndmask_b32_e32 v145, v20, v22, vcc
	v_cndmask_b32_e32 v146, v21, v23, vcc
	v_mov_b32_dpp v143, v143 quad_perm:[1,0,3,2] row_mask:0xf bank_mask:0xf bound_ctrl:1
	v_mov_b32_dpp v144, v144 quad_perm:[1,0,3,2] row_mask:0xf bank_mask:0xf bound_ctrl:1
	v_mov_b32_dpp v145, v145 quad_perm:[1,0,3,2] row_mask:0xf bank_mask:0xf bound_ctrl:1
	v_mov_b32_dpp v146, v146 quad_perm:[1,0,3,2] row_mask:0xf bank_mask:0xf bound_ctrl:1
	v_cndmask_b32_e32 v28, v143, v28, vcc
	v_cndmask_b32_e32 v30, v30, v143, vcc
	v_cndmask_b32_e32 v29, v144, v29, vcc
	v_cndmask_b32_e32 v31, v31, v144, vcc
	v_cvt_pk_bf16_f32 v28, v28, v30
	v_cvt_pk_bf16_f32 v29, v29, v31
	ds_write_b32 v131, v28 offset:16896
	ds_write_b32 v131, v29 offset:17424
	v_cndmask_b32_e32 v20, v145, v20, vcc
	v_cndmask_b32_e32 v22, v22, v145, vcc
	v_cndmask_b32_e32 v21, v146, v21, vcc
	v_cndmask_b32_e32 v23, v23, v146, vcc
	v_cvt_pk_bf16_f32 v20, v20, v22
	v_cvt_pk_bf16_f32 v21, v21, v23
	ds_write_b32 v131, v20 offset:16928
	ds_write_b32 v131, v21 offset:17456
	v_cndmask_b32_e32 v143, v24, v26, vcc
	v_cndmask_b32_e32 v144, v25, v27, vcc
	v_cndmask_b32_e32 v145, v16, v18, vcc
	v_cndmask_b32_e32 v146, v17, v19, vcc
	v_mov_b32_dpp v143, v143 quad_perm:[1,0,3,2] row_mask:0xf bank_mask:0xf bound_ctrl:1
	v_mov_b32_dpp v144, v144 quad_perm:[1,0,3,2] row_mask:0xf bank_mask:0xf bound_ctrl:1
	v_mov_b32_dpp v145, v145 quad_perm:[1,0,3,2] row_mask:0xf bank_mask:0xf bound_ctrl:1
	v_mov_b32_dpp v146, v146 quad_perm:[1,0,3,2] row_mask:0xf bank_mask:0xf bound_ctrl:1
	v_cndmask_b32_e32 v24, v143, v24, vcc
	v_cndmask_b32_e32 v26, v26, v143, vcc
	v_cndmask_b32_e32 v25, v144, v25, vcc
	v_cndmask_b32_e32 v27, v27, v144, vcc
	v_cvt_pk_bf16_f32 v24, v24, v26
	v_cvt_pk_bf16_f32 v25, v25, v27
	ds_write_b32 v131, v24 offset:17152
	ds_write_b32 v131, v25 offset:17680
	v_cndmask_b32_e32 v16, v145, v16, vcc
	v_cndmask_b32_e32 v18, v18, v145, vcc
	v_cndmask_b32_e32 v17, v146, v17, vcc
	v_cndmask_b32_e32 v19, v19, v146, vcc
	v_cvt_pk_bf16_f32 v16, v16, v18
	v_cvt_pk_bf16_f32 v17, v17, v19
	ds_write_b32 v131, v16 offset:17184
	ds_write_b32 v131, v17 offset:17712
	v_cndmask_b32_e32 v143, v12, v14, vcc
	v_cndmask_b32_e32 v144, v13, v15, vcc
	v_cndmask_b32_e32 v145, v4, v6, vcc
	v_cndmask_b32_e32 v146, v5, v7, vcc
	v_mov_b32_dpp v143, v143 quad_perm:[1,0,3,2] row_mask:0xf bank_mask:0xf bound_ctrl:1
	v_mov_b32_dpp v144, v144 quad_perm:[1,0,3,2] row_mask:0xf bank_mask:0xf bound_ctrl:1
	v_mov_b32_dpp v145, v145 quad_perm:[1,0,3,2] row_mask:0xf bank_mask:0xf bound_ctrl:1
	v_mov_b32_dpp v146, v146 quad_perm:[1,0,3,2] row_mask:0xf bank_mask:0xf bound_ctrl:1
	v_cndmask_b32_e32 v12, v143, v12, vcc
	v_cndmask_b32_e32 v14, v14, v143, vcc
	v_cndmask_b32_e32 v13, v144, v13, vcc
	v_cndmask_b32_e32 v15, v15, v144, vcc
	v_cvt_pk_bf16_f32 v12, v12, v14
	v_cvt_pk_bf16_f32 v13, v13, v15
	ds_write_b32 v131, v12 offset:25344
	ds_write_b32 v131, v13 offset:25872
	v_cndmask_b32_e32 v4, v145, v4, vcc
	v_cndmask_b32_e32 v6, v6, v145, vcc
	v_cndmask_b32_e32 v5, v146, v5, vcc
	v_cndmask_b32_e32 v7, v7, v146, vcc
	v_cvt_pk_bf16_f32 v4, v4, v6
	v_cvt_pk_bf16_f32 v5, v5, v7
	ds_write_b32 v131, v4 offset:25376
	ds_write_b32 v131, v5 offset:25904
	v_cndmask_b32_e32 v143, v8, v10, vcc
	v_cndmask_b32_e32 v144, v9, v11, vcc
	v_cndmask_b32_e32 v145, v0, v2, vcc
	v_cndmask_b32_e32 v146, v1, v3, vcc
	v_mov_b32_dpp v143, v143 quad_perm:[1,0,3,2] row_mask:0xf bank_mask:0xf bound_ctrl:1
	v_mov_b32_dpp v144, v144 quad_perm:[1,0,3,2] row_mask:0xf bank_mask:0xf bound_ctrl:1
	v_mov_b32_dpp v145, v145 quad_perm:[1,0,3,2] row_mask:0xf bank_mask:0xf bound_ctrl:1
	v_mov_b32_dpp v146, v146 quad_perm:[1,0,3,2] row_mask:0xf bank_mask:0xf bound_ctrl:1
	v_cndmask_b32_e32 v8, v143, v8, vcc
	v_cndmask_b32_e32 v10, v10, v143, vcc
	v_cndmask_b32_e32 v9, v144, v9, vcc
	v_cndmask_b32_e32 v11, v11, v144, vcc
	v_cvt_pk_bf16_f32 v8, v8, v10
	v_cvt_pk_bf16_f32 v9, v9, v11
	ds_write_b32 v131, v8 offset:25600
	ds_write_b32 v131, v9 offset:26128
	v_cndmask_b32_e32 v0, v145, v0, vcc
	v_cndmask_b32_e32 v2, v2, v145, vcc
	v_cndmask_b32_e32 v1, v146, v1, vcc
	v_cndmask_b32_e32 v3, v3, v146, vcc
	v_cvt_pk_bf16_f32 v0, v0, v2
	v_cvt_pk_bf16_f32 v1, v1, v3
	ds_write_b32 v131, v0 offset:25632
	ds_write_b32 v131, v1 offset:26160
	s_waitcnt lgkmcnt(0)
	s_barrier
	ds_read_b128 v[0:3], v133
	ds_read_b128 v[4:7], v133 offset:8448
	ds_read_b128 v[8:11], v133 offset:16896
	ds_read_b128 v[12:15], v133 offset:25344
	ds_read_b128 v[16:19], v133 offset:33792
	ds_read_b128 v[20:23], v133 offset:42240
	ds_read_b128 v[24:27], v133 offset:50688
	ds_read_b128 v[28:31], v133 offset:59136
	s_waitcnt lgkmcnt(7)
	global_store_dwordx4 v155, v[0:3], s[0:1]
	s_waitcnt lgkmcnt(6)
	global_store_dwordx4 v156, v[4:7], s[0:1]
	s_waitcnt lgkmcnt(5)
	global_store_dwordx4 v157, v[8:11], s[0:1]
	s_waitcnt lgkmcnt(4)
	global_store_dwordx4 v158, v[12:15], s[0:1]
	s_waitcnt lgkmcnt(3)
	global_store_dwordx4 v159, v[16:19], s[0:1]
	s_waitcnt lgkmcnt(2)
	global_store_dwordx4 v160, v[20:23], s[0:1]
	s_waitcnt lgkmcnt(1)
	global_store_dwordx4 v161, v[24:27], s[0:1]
	s_waitcnt lgkmcnt(0)
	global_store_dwordx4 v162, v[28:31], s[0:1]
	s_add_i32 s47, s47, s94
	s_add_i32 s3, s3, s40
	s_add_i32 s41, s41, s42
	s_cmpk_lt_i32 s47, 0x500
	s_nop 0
	s_barrier
	s_cbranch_scc0 .LBB0_230
